# compressed passes 1 and 2: K tile copies removed, MFMAs read the prefetch registers directly and the next K tile is loaded right after the QK MFMAs
# baseline (speedup 1.0000x reference)
; #define LAS __attribute__((address_space(3)))
; __device__ __forceinline__ void nsa_unit(const Params& p, int bg, int jq, LAS unsigned char* lds, int wave, int lane, bool build_lut) {
;     ...
; #pragma unroll
;     for (int e = 0; e < 8; ++e) *(LAS f32x4*)(imp + 4 * (lane + 64 * e)) = (f32x4){0.f, 0.f, 0.f, 0.f};
;     {
;         const int k = lane & 7; unsigned w = 0u;
;         if (k == 0) w |= 1u;
;         if ((jq >> 5) == k) w |= 1u << (jq & 31);
;         if (jq >= 1 && ((jq - 1) >> 5) == k) w |= 1u << ((jq - 1) & 31);
;         selw[lane] = w;
;     }
;     asm volatile("s_waitcnt lgkmcnt(0)" ::: "memory");
;     __builtin_amdgcn_wave_barrier();
;     const LAS float* lutr = lut + r * 132;
;     const float lutfar = lutr[128];
;     bf16x8 qf[4];
; #pragma unroll
;     for (int ks = 0; ks < 4; ++ks) qf[ks] = *(const bf16x8*)(qb + tok * 512 + (g * 4 + r) * 64 + ks * 16 + h * 8);
;     const float g0 = gates[tok * 24 + (g * 4 + r) * 3 + 0], g1 = gates[tok * 24 + (g * 4 + r) * 3 + 1], g2 = gates[tok * 24 + (g * 4 + r) * 3 + 2];
;     f32x16 oa0, oa1;
;     bf16x8 kf[4], kn[4], vf[2][2];
;     {
;         const int jmaxw = (tq0 + 7 - 31) >> 4;
;         const int ntile = (jmaxw >= 0) ? (jmaxw >> 5) + 1 : 0;
;         float m = -1e30f, l = 0.f;
;         if (ntile > 0) load_k(kn, kcmp, lane);
;         for (int T = 0; T < ntile; ++T) {
; #pragma unroll
;             for (int ks = 0; ks < 4; ++ks) kf[ks] = kn[ks];
;             if (T + 1 < ntile) load_k(kn, kcmp + (size_t)(T + 1) * 2048, lane);
.LBB0_1051:
	s_or_b64 exec, exec, s[4:5]
	s_lshl_b32 s4, s26, 6
	s_and_b32 s28, s4, 0xffffe000
	s_lshl_b32 s4, s27, 6
	s_and_b32 s4, s4, 0x80
	s_bitcmp0_b32 s27, 0
	v_readlane_b32 s5, v253, 17
	v_readlane_b32 s6, v253, 18
	s_cselect_b32 s29, s5, s6
	s_add_i32 s20, s29, s4
	s_waitcnt lgkmcnt(0)
	s_add_u32 s16, s14, 0xa900000
	s_addc_u32 s17, s15, 0
	v_readlane_b32 s4, v253, 56
	s_add_u32 s4, s14, s4
	s_addc_u32 s5, s15, 0
	s_add_u32 s6, s4, 0x14300000
	s_addc_u32 s7, s5, 0
	s_lshl_b32 s4, s20, 6
	s_lshl_b32 s30, s12, 3
	v_bfe_u32 v158, v145, 2, 3
	s_add_i32 s31, s30, s4
	s_add_i32 s34, s18, 0
	v_or_b32_e32 v2, s31, v158
	s_ashr_i32 s8, s20, 5
	s_lshl_b32 s9, 1, s29
	v_ashrrev_i32_e32 v3, 31, v2
	v_and_b32_e32 v118, 7, v145
	s_cmp_gt_i32 s20, 0
	v_lshl_add_u64 v[182:183], v[2:3], 0, s[90:91]
	s_mov_b32 s73, s72
	v_mov_b32_e32 v3, s9
	v_cmp_eq_u32_e32 vcc, s8, v118
	s_cselect_b64 s[8:9], -1, 0
	s_add_i32 s10, s20, -1
	v_lshlrev_b32_e32 v114, 4, v145
	s_mov_b32 s74, s72
	s_mov_b32 s75, s72
	v_mov_b64_e32 v[4:5], s[72:73]
	s_lshr_b32 s11, s10, 5
	v_add_u32_e32 v2, s34, v114
	v_mov_b64_e32 v[6:7], s[74:75]
	v_cndmask_b32_e32 v3, 0, v3, vcc
	v_cmp_eq_u32_e32 vcc, s11, v118
	s_lshl_b32 s10, 1, s10
	ds_write_b128 v2, v[4:7]
	ds_write_b128 v2, v[4:7] offset:1024
	ds_write_b128 v2, v[4:7] offset:2048
	ds_write_b128 v2, v[4:7] offset:3072
	ds_write_b128 v2, v[4:7] offset:4096
	ds_write_b128 v2, v[4:7] offset:5120
	ds_write_b128 v2, v[4:7] offset:6144
	ds_write_b128 v2, v[4:7] offset:7168
	v_cmp_eq_u32_e64 s[4:5], 0, v118
	v_mov_b32_e32 v4, s10
	s_and_b64 vcc, s[8:9], vcc
	v_cndmask_b32_e64 v2, 0, 1, s[4:5]
	v_cndmask_b32_e32 v4, 0, v4, vcc
	v_or3_b32 v2, v3, v2, v4
	v_lshl_add_u32 v159, v145, 2, s34
	v_ashrrev_i32_e32 v179, 5, v145
	v_and_b32_e32 v1, 3, v145
	ds_write_b32 v159, v2 offset:8192
	v_and_b32_e32 v238, 3, v145
	v_mul_u32_u24_e32 v238, 0x210, v238
	v_add_u32_e32 v238, s34, v238
	ds_read_b32 v239, v238 offset:8960
	v_bfe_u32 v240, v145, 2, 2
	v_min_u32_e32 v240, 2, v240
	v_lshl_add_u32 v238, v240, 2, v238
	s_waitcnt lgkmcnt(0)
	ds_write_b32 v238, v239 offset:8964
	v_lshlrev_b64 v[2:3], 10, v[182:183]
	v_readlane_b32 s8, v253, 57
	v_lshl_add_u64 v[140:141], s[16:17], 0, v[2:3]
	v_mov_b32_e32 v3, v0
	v_lshl_or_b32 v2, v1, 7, s8
	v_lshlrev_b32_e32 v142, 3, v179
	v_lshl_add_u64 v[2:3], v[140:141], 0, v[2:3]
	v_ashrrev_i32_e32 v143, 31, v142
	v_lshl_add_u64 v[2:3], v[142:143], 1, v[2:3]
	s_waitcnt lgkmcnt(0)
	global_load_dwordx4 v[66:69], v[2:3], off
	global_load_dwordx4 v[70:73], v[2:3], off offset:32
	global_load_dwordx4 v[74:77], v[2:3], off offset:64
	global_load_dwordx4 v[78:81], v[2:3], off offset:96
	v_or_b32_e32 v115, s3, v1
	v_mov_b64_e32 v[2:3], s[14:15]
	s_movk_i32 s10, 0x60
	v_mul_u32_u24_e32 v4, 3, v115
	v_mad_u64_u32 v[2:3], s[8:9], v182, s10, v[2:3]
	v_mad_i32_i24 v3, v183, s10, v3
	v_lshlrev_b32_e32 v4, 2, v4
	v_mov_b32_e32 v5, v0
	v_lshl_add_u64 v[2:3], v[2:3], 0, v[4:5]
	v_add_co_u32_e32 v2, vcc, 0x13b00000, v2
	s_movk_i32 s8, 0x210
	s_nop 0
	v_addc_co_u32_e32 v3, vcc, 0, v3, vcc
	global_load_dwordx3 v[176:178], v[2:3], off
	v_mov_b32_e32 v2, s34
	v_mad_u32_u24 v231, v1, s8, v2
	s_sub_i32 s8, s31, 24
	s_lshr_b32 s8, s8, 9
	ds_read_b32 v184, v231 offset:8960
	s_add_i32 s12, s8, 1
	s_cmp_gt_i32 s31, 23
	s_cselect_b64 s[8:9], -1, 0
	s_and_b64 s[10:11], s[8:9], exec
	s_cselect_b32 s21, s12, 0
	s_cmp_lt_i32 s31, 24
	s_cbranch_scc1 .LBB0_1092
	v_lshlrev_b32_e32 v2, 3, v145
	v_ashrrev_i32_e32 v3, 31, v2
	v_lshlrev_b64 v[18:19], 1, v[2:3]
	v_lshl_add_u64 v[14:15], s[6:7], 0, v[18:19]
	global_load_dwordx4 v[2:5], v[14:15], off
	global_load_dwordx4 v[6:9], v[14:15], off offset:1024
	global_load_dwordx4 v[10:13], v[14:15], off offset:2048
	s_nop 0
	global_load_dwordx4 v[14:17], v[14:15], off offset:3072
	s_lshl_b32 s10, s29, 6
	s_add_i32 s10, s28, s10
	s_add_i32 s11, s10, s30
	s_sub_i32 s11, s11, 24
	s_lshr_b32 s12, s11, 9
	v_add_u32_e32 v21, s10, v158
	s_sub_i32 s13, s10, 31
	v_readlane_b32 s10, v253, 52
	s_add_u32 s10, s14, s10
	v_lshlrev_b32_e32 v20, 6, v179
	s_addc_u32 s11, s15, 0
	s_waitcnt lgkmcnt(0)
	v_mov_b32_e32 v185, v184
	s_waitcnt vmcnt(9)
	v_mov_b32_e32 v50, v184
	v_mov_b32_e32 v51, v184
	v_mov_b32_e32 v52, v184
	v_mov_b32_e32 v53, v184
	v_mov_b32_e32 v54, v184
	v_mov_b32_e32 v55, v184
	v_mov_b32_e32 v56, v184
	v_mov_b32_e32 v57, v184
	v_mov_b32_e32 v58, v184
	v_mov_b32_e32 v59, v184
	v_mov_b32_e32 v60, v184
	v_mov_b32_e32 v61, v184
	v_mov_b32_e32 v62, v184
	v_mov_b32_e32 v63, v184
	v_sub_u32_e32 v82, v21, v20
	v_lshl_add_u64 v[64:65], s[10:11], 0, v[18:19]
	v_mov_b32_e32 v83, 0
	v_mov_b32_e32 v84, 0xf149f2ca
	s_mov_b32 s19, -1
	s_waitcnt vmcnt(3)
	v_mov_b64_e32 v[36:37], v[4:5]
	s_waitcnt vmcnt(2)
	v_mov_b64_e32 v[40:41], v[8:9]
	s_waitcnt vmcnt(1)
	v_mov_b64_e32 v[44:45], v[12:13]
	s_waitcnt vmcnt(0)
	v_mov_b64_e32 v[48:49], v[16:17]
	v_mov_b64_e32 v[34:35], v[2:3]
	v_mov_b64_e32 v[38:39], v[6:7]
	v_mov_b64_e32 v[42:43], v[10:11]
	v_mov_b64_e32 v[46:47], v[14:15]
	s_branch .LBB0_1055
.LBB0_1053:
	v_mov_b32_e32 v84, v85
	v_mov_b32_e32 v83, v86
	s_waitcnt vmcnt(0)
; #define LAS __attribute__((address_space(3)))
; template <int STRIDE> __device__ __forceinline__ void score_tile(f32x16& s, int dl, int dmax, bool lane_ok, bool fast, float lutfar, const LAS float* lutr) {
;     if (fast) {
; #pragma unroll
;         for (int i = 0; i < 16; ++i) s[i] = lane_ok ? (s[i] + lutfar) : NEG_INF;
;     } else {
; #pragma unroll
;         for (int i = 0; i < 16; ++i) {
;             const int d = dl - STRIDE * ((i & 3) + 8 * (i >> 2));
;             const bool ok = lane_ok && d >= 0 && d < dmax;
;             const int di = min(max(d, 0), 128);
;             s[i] = ok ? (s[i] + lutr[di]) : NEG_INF;
;         }
;     }
; __device__ __forceinline__ void nsa_unit(const Params& p, int bg, int jq, LAS unsigned char* lds, int wave, int lane, bool build_lut) {
;     ...
;         for (int T = 0; T < ntile; ++T) {
; #pragma unroll
;             for (int ks = 0; ks < 4; ++ks) kf[ks] = kn[ks];
;             if (T + 1 < ntile) load_k(kn, kcmp + (size_t)(T + 1) * 2048, lane);
;             f32x16 s = qk_tile(kf, qf);
;             const int base = 512 * T + 31;
;             const bool fast = (tq0 - base - 16 * 31) >= 128;
;             score_tile<16>(s, tq - base - 64 * h, 1 << 30, true, fast, lutfar, lutr);
.LBB0_1055:
	v_mfma_f32_32x32x16_bf16 v[18:33], v[34:37], v[66:69], 0
	s_add_i32 s22, s30, s13
	s_mov_b64 s[10:11], -1
	v_mfma_f32_32x32x16_bf16 v[18:33], v[38:41], v[70:73], v[18:33]
	v_mfma_f32_32x32x16_bf16 v[18:33], v[42:45], v[74:77], v[18:33]
	v_mfma_f32_32x32x16_bf16 v[18:33], v[46:49], v[78:81], v[18:33]
	s_add_i32 s100, s19, 2
	s_cmp_lt_u32 s100, s21
	s_cbranch_scc0 .Lp1_noload
	global_load_dwordx4 v[34:37], v[64:65], off offset:-3072
	global_load_dwordx4 v[38:41], v[64:65], off offset:-2048
	global_load_dwordx4 v[42:45], v[64:65], off offset:-1024
	global_load_dwordx4 v[46:49], v[64:65], off
.Lp1_noload:
	s_cmpk_gt_i32 s22, 0x26f
	s_cbranch_scc1 .LBB0_1089
	v_add_u32_e32 v85, s30, v82
	v_mov_b32_e32 v240, 0xff800000
	v_subrev_u32_e32 v2, 31, v85
	v_min_u32_e32 v2, 0x80, v2
	v_lshl_add_u32 v2, v2, 2, v231
	ds_read_b32 v2, v2 offset:8448
	v_subrev_u32_e32 v3, 47, v85
	v_min_u32_e32 v3, 0x80, v3
	v_lshl_add_u32 v3, v3, 2, v231
	ds_read_b32 v3, v3 offset:8448
	v_subrev_u32_e32 v4, 63, v85
	v_min_u32_e32 v4, 0x80, v4
	v_lshl_add_u32 v4, v4, 2, v231
	ds_read_b32 v4, v4 offset:8448
	v_add_u32_e32 v5, 0xffffffb1, v85
	v_min_u32_e32 v5, 0x80, v5
	v_lshl_add_u32 v5, v5, 2, v231
	ds_read_b32 v5, v5 offset:8448
	v_add_u32_e32 v6, 0xffffff61, v85
	v_min_u32_e32 v6, 0x80, v6
	v_lshl_add_u32 v6, v6, 2, v231
	ds_read_b32 v6, v6 offset:8448
	v_add_u32_e32 v7, 0xffffff51, v85
	v_min_u32_e32 v7, 0x80, v7
	v_lshl_add_u32 v7, v7, 2, v231
	ds_read_b32 v7, v7 offset:8448
	v_add_u32_e32 v8, 0xffffff41, v85
	v_min_u32_e32 v8, 0x80, v8
	v_lshl_add_u32 v8, v8, 2, v231
	ds_read_b32 v8, v8 offset:8448
	v_add_u32_e32 v9, 0xffffff31, v85
	v_min_u32_e32 v9, 0x80, v9
	v_lshl_add_u32 v9, v9, 2, v231
	ds_read_b32 v9, v9 offset:8448
	v_add_u32_e32 v10, 0xfffffee1, v85
	v_min_u32_e32 v10, 0x80, v10
	v_lshl_add_u32 v10, v10, 2, v231
	ds_read_b32 v10, v10 offset:8448
	v_add_u32_e32 v11, 0xfffffed1, v85
	v_min_u32_e32 v11, 0x80, v11
	v_lshl_add_u32 v11, v11, 2, v231
	ds_read_b32 v11, v11 offset:8448
	v_add_u32_e32 v12, 0xfffffec1, v85
	v_min_u32_e32 v12, 0x80, v12
	v_lshl_add_u32 v12, v12, 2, v231
	ds_read_b32 v12, v12 offset:8448
	v_add_u32_e32 v13, 0xfffffeb1, v85
	v_min_u32_e32 v13, 0x80, v13
	v_lshl_add_u32 v13, v13, 2, v231
	ds_read_b32 v13, v13 offset:8448
	v_add_u32_e32 v14, 0xfffffe61, v85
	v_min_u32_e32 v14, 0x80, v14
	v_lshl_add_u32 v14, v14, 2, v231
	ds_read_b32 v14, v14 offset:8448
	v_add_u32_e32 v15, 0xfffffe51, v85
	v_min_u32_e32 v15, 0x80, v15
	v_lshl_add_u32 v15, v15, 2, v231
	ds_read_b32 v15, v15 offset:8448
	v_add_u32_e32 v16, 0xfffffe41, v85
	v_min_u32_e32 v16, 0x80, v16
	v_lshl_add_u32 v16, v16, 2, v231
	ds_read_b32 v16, v16 offset:8448
	v_add_u32_e32 v17, 0xfffffe31, v85
	v_min_u32_e32 v17, 0x80, v17
	v_lshl_add_u32 v17, v17, 2, v231
	ds_read_b32 v17, v17 offset:8448
	v_subrev_u32_e32 v238, 31, v85
	s_waitcnt lgkmcnt(15)
	v_cmp_gt_u32_e32 vcc, 2.0, v238
	v_subrev_u32_e32 v239, 47, v85
	v_add_f32_e32 v2, v18, v2
	v_cndmask_b32_e32 v2, v240, v2, vcc
	v_cmp_gt_u32_e32 vcc, 2.0, v239
	v_subrev_u32_e32 v238, 63, v85
	s_waitcnt lgkmcnt(14)
	v_add_f32_e32 v3, v19, v3
	v_cndmask_b32_e32 v3, v240, v3, vcc
	v_cmp_gt_u32_e32 vcc, 2.0, v238
	v_add_u32_e32 v239, 0xffffffb1, v85
	s_waitcnt lgkmcnt(13)
	v_add_f32_e32 v4, v20, v4
	v_cndmask_b32_e32 v4, v240, v4, vcc
	v_cmp_gt_u32_e32 vcc, 2.0, v239
	v_add_u32_e32 v238, 0xffffff61, v85
	s_waitcnt lgkmcnt(12)
	v_add_f32_e32 v5, v21, v5
	v_cndmask_b32_e32 v5, v240, v5, vcc
	v_cmp_gt_u32_e32 vcc, 2.0, v238
	v_add_u32_e32 v239, 0xffffff51, v85
	s_waitcnt lgkmcnt(11)
	v_add_f32_e32 v6, v22, v6
	v_cndmask_b32_e32 v6, v240, v6, vcc
	v_cmp_gt_u32_e32 vcc, 2.0, v239
	v_add_u32_e32 v238, 0xffffff41, v85
	s_waitcnt lgkmcnt(10)
	v_add_f32_e32 v7, v23, v7
	v_cndmask_b32_e32 v7, v240, v7, vcc
	v_cmp_gt_u32_e32 vcc, 2.0, v238
	v_add_u32_e32 v239, 0xffffff31, v85
	s_waitcnt lgkmcnt(9)
	v_add_f32_e32 v8, v24, v8
	v_cndmask_b32_e32 v8, v240, v8, vcc
	v_cmp_gt_u32_e32 vcc, 2.0, v239
	v_add_u32_e32 v238, 0xfffffee1, v85
	s_waitcnt lgkmcnt(8)
	v_add_f32_e32 v9, v25, v9
	v_cndmask_b32_e32 v9, v240, v9, vcc
	v_cmp_gt_u32_e32 vcc, 2.0, v238
	v_add_u32_e32 v239, 0xfffffed1, v85
	s_waitcnt lgkmcnt(7)
	v_add_f32_e32 v10, v26, v10
	v_cndmask_b32_e32 v10, v240, v10, vcc
	v_cmp_gt_u32_e32 vcc, 2.0, v239
	v_add_u32_e32 v238, 0xfffffec1, v85
	s_waitcnt lgkmcnt(6)
	v_add_f32_e32 v11, v27, v11
	v_cndmask_b32_e32 v11, v240, v11, vcc
	v_cmp_gt_u32_e32 vcc, 2.0, v238
	v_add_u32_e32 v239, 0xfffffeb1, v85
	s_waitcnt lgkmcnt(5)
	v_add_f32_e32 v12, v28, v12
	v_cndmask_b32_e32 v12, v240, v12, vcc
	v_cmp_gt_u32_e32 vcc, 2.0, v239
	v_add_u32_e32 v238, 0xfffffe61, v85
	s_waitcnt lgkmcnt(4)
	v_add_f32_e32 v13, v29, v13
	v_cndmask_b32_e32 v13, v240, v13, vcc
	v_cmp_gt_u32_e32 vcc, 2.0, v238
	v_add_u32_e32 v239, 0xfffffe51, v85
	s_waitcnt lgkmcnt(3)
	v_add_f32_e32 v14, v30, v14
	v_cndmask_b32_e32 v14, v240, v14, vcc
	v_cmp_gt_u32_e32 vcc, 2.0, v239
	v_add_u32_e32 v238, 0xfffffe41, v85
	s_waitcnt lgkmcnt(2)
	v_add_f32_e32 v15, v31, v15
	v_cndmask_b32_e32 v15, v240, v15, vcc
	v_cmp_gt_u32_e32 vcc, 2.0, v238
	v_add_u32_e32 v239, 0xfffffe31, v85
	s_waitcnt lgkmcnt(1)
	v_add_f32_e32 v16, v32, v16
	v_cndmask_b32_e32 v16, v240, v16, vcc
	v_cmp_gt_u32_e32 vcc, 2.0, v239
	s_nop 0
	s_waitcnt lgkmcnt(0)
	v_add_f32_e32 v17, v33, v17
	v_cndmask_b32_e32 v17, v240, v17, vcc
	s_mov_b64 s[10:11], 0

; __device__ __forceinline__ float fast_exp2(float x) { return __builtin_amdgcn_exp2f(x); }
; __device__ __forceinline__ void nsa_unit(const Params& p, int bg, int jq, LAS unsigned char* lds, int wave, int lane, bool build_lut) {
;     ...
;         for (int T = 0; T < ntile; ++T) {
; #pragma unroll
;             for (int ks = 0; ks < 4; ++ks) kf[ks] = kn[ks];
;             load_v(vf, vcmpT + (size_t)T * 2048, lane);
;             if (T + 1 < ntile) load_k(kn, kcmp + (size_t)(T + 1) * 2048, lane);
;             f32x16 s = qk_tile(kf, qf);
;             const int base = 512 * T + 31;
;             const bool fast = (tq0 - base - 16 * 31) >= 128;
;             if (fast) {
; #pragma unroll
;                 for (int i = 0; i < 16; ++i) s[i] = fast_exp2(s[i] - c2f);
;             } else {
;                 score_tile<16>(s, tq - base - 64 * h, 1 << 30, true, false, lutfar, lutr);
; #pragma unroll
;                 for (int i = 0; i < 16; ++i) s[i] = fast_exp2(s[i] - c2);
;             }
.LBB0_1097:
	s_waitcnt vmcnt(4)
	v_mfma_f32_32x32x16_bf16 v[34:49], v[82:85], v[66:69], 0
	s_add_i32 s25, s30, s23
	s_mov_b64 s[18:19], -1
	v_mfma_f32_32x32x16_bf16 v[34:49], v[86:89], v[70:73], v[34:49]
	v_mfma_f32_32x32x16_bf16 v[34:49], v[90:93], v[74:77], v[34:49]
	v_mfma_f32_32x32x16_bf16 v[34:49], v[94:97], v[78:81], v[34:49]
	s_add_i32 s100, s24, 2
	s_cmp_lt_u32 s100, s21
	s_cbranch_scc0 .Lp2_noload
	global_load_dwordx4 v[82:85], v[116:117], off
	global_load_dwordx4 v[86:89], v[116:117], off offset:1024
	global_load_dwordx4 v[90:93], v[116:117], off offset:2048
	global_load_dwordx4 v[94:97], v[116:117], off offset:3072
.Lp2_noload:
	s_cmpk_lt_i32 s25, 0x270
	s_cbranch_scc0 .LBB0_1131
	v_add_u32_e32 v52, s30, v122
	v_mov_b32_e32 v240, 0xff800000
	v_subrev_u32_e32 v50, 31, v52
	v_min_u32_e32 v50, 0x80, v50
	v_lshl_add_u32 v50, v50, 2, v231
	ds_read_b32 v50, v50 offset:8448
	v_subrev_u32_e32 v51, 47, v52
	v_min_u32_e32 v51, 0x80, v51
	v_lshl_add_u32 v51, v51, 2, v231
	ds_read_b32 v51, v51 offset:8448
	v_subrev_u32_e32 v54, 63, v52
	v_min_u32_e32 v54, 0x80, v54
	v_lshl_add_u32 v54, v54, 2, v231
	ds_read_b32 v54, v54 offset:8448
	v_add_u32_e32 v53, 0xffffffb1, v52
	v_min_u32_e32 v53, 0x80, v53
	v_lshl_add_u32 v53, v53, 2, v231
	ds_read_b32 v53, v53 offset:8448
	v_add_u32_e32 v56, 0xffffff61, v52
	v_min_u32_e32 v56, 0x80, v56
	v_lshl_add_u32 v56, v56, 2, v231
	ds_read_b32 v56, v56 offset:8448
	v_add_u32_e32 v55, 0xffffff51, v52
	v_min_u32_e32 v55, 0x80, v55
	v_lshl_add_u32 v55, v55, 2, v231
	ds_read_b32 v55, v55 offset:8448
	v_add_u32_e32 v58, 0xffffff41, v52
	v_min_u32_e32 v58, 0x80, v58
	v_lshl_add_u32 v58, v58, 2, v231
	ds_read_b32 v58, v58 offset:8448
	v_add_u32_e32 v57, 0xffffff31, v52
	v_min_u32_e32 v57, 0x80, v57
	v_lshl_add_u32 v57, v57, 2, v231
	ds_read_b32 v57, v57 offset:8448
	v_add_u32_e32 v60, 0xfffffee1, v52
	v_min_u32_e32 v60, 0x80, v60
	v_lshl_add_u32 v60, v60, 2, v231
	ds_read_b32 v60, v60 offset:8448
	v_add_u32_e32 v59, 0xfffffed1, v52
	v_min_u32_e32 v59, 0x80, v59
	v_lshl_add_u32 v59, v59, 2, v231
	ds_read_b32 v59, v59 offset:8448
	v_add_u32_e32 v62, 0xfffffec1, v52
	v_min_u32_e32 v62, 0x80, v62
	v_lshl_add_u32 v62, v62, 2, v231
	ds_read_b32 v62, v62 offset:8448
	v_add_u32_e32 v61, 0xfffffeb1, v52
	v_min_u32_e32 v61, 0x80, v61
	v_lshl_add_u32 v61, v61, 2, v231
	ds_read_b32 v61, v61 offset:8448
	v_add_u32_e32 v64, 0xfffffe61, v52
	v_min_u32_e32 v64, 0x80, v64
	v_lshl_add_u32 v64, v64, 2, v231
	ds_read_b32 v64, v64 offset:8448
	v_add_u32_e32 v63, 0xfffffe51, v52
	v_min_u32_e32 v63, 0x80, v63
	v_lshl_add_u32 v63, v63, 2, v231
	ds_read_b32 v63, v63 offset:8448
	v_add_u32_e32 v124, 0xfffffe41, v52
	v_min_u32_e32 v124, 0x80, v124
	v_lshl_add_u32 v124, v124, 2, v231
	ds_read_b32 v124, v124 offset:8448
	v_add_u32_e32 v65, 0xfffffe31, v52
	v_min_u32_e32 v65, 0x80, v65
	v_lshl_add_u32 v65, v65, 2, v231
	ds_read_b32 v65, v65 offset:8448
	v_subrev_u32_e32 v238, 31, v52
	s_waitcnt lgkmcnt(15)
	v_cmp_gt_u32_e32 vcc, 2.0, v238
	v_subrev_u32_e32 v239, 47, v52
	v_add_f32_e32 v50, v34, v50
	v_cndmask_b32_e32 v50, v240, v50, vcc
	v_cmp_gt_u32_e32 vcc, 2.0, v239
	v_subrev_u32_e32 v238, 63, v52
	s_waitcnt lgkmcnt(14)
	v_add_f32_e32 v51, v35, v51
	v_cndmask_b32_e32 v51, v240, v51, vcc
	v_cmp_gt_u32_e32 vcc, 2.0, v238
	v_add_u32_e32 v239, 0xffffffb1, v52
	s_waitcnt lgkmcnt(13)
	v_add_f32_e32 v54, v36, v54
	v_cndmask_b32_e32 v54, v240, v54, vcc
	v_cmp_gt_u32_e32 vcc, 2.0, v239
	v_add_u32_e32 v238, 0xffffff61, v52
	s_waitcnt lgkmcnt(12)
	v_add_f32_e32 v53, v37, v53
	v_cndmask_b32_e32 v53, v240, v53, vcc
	v_cmp_gt_u32_e32 vcc, 2.0, v238
	v_add_u32_e32 v239, 0xffffff51, v52
	s_waitcnt lgkmcnt(11)
	v_add_f32_e32 v56, v38, v56
	v_cndmask_b32_e32 v56, v240, v56, vcc
	v_cmp_gt_u32_e32 vcc, 2.0, v239
	v_add_u32_e32 v238, 0xffffff41, v52
	s_waitcnt lgkmcnt(10)
	v_add_f32_e32 v55, v39, v55
	v_cndmask_b32_e32 v55, v240, v55, vcc
	v_cmp_gt_u32_e32 vcc, 2.0, v238
	v_add_u32_e32 v239, 0xffffff31, v52
	s_waitcnt lgkmcnt(9)
	v_add_f32_e32 v58, v40, v58
	v_cndmask_b32_e32 v58, v240, v58, vcc
	v_cmp_gt_u32_e32 vcc, 2.0, v239
	v_add_u32_e32 v238, 0xfffffee1, v52
	s_waitcnt lgkmcnt(8)
	v_add_f32_e32 v57, v41, v57
	v_cndmask_b32_e32 v57, v240, v57, vcc
	v_cmp_gt_u32_e32 vcc, 2.0, v238
	v_add_u32_e32 v239, 0xfffffed1, v52
	s_waitcnt lgkmcnt(7)
	v_add_f32_e32 v60, v42, v60
	v_cndmask_b32_e32 v60, v240, v60, vcc
	v_cmp_gt_u32_e32 vcc, 2.0, v239
	v_add_u32_e32 v238, 0xfffffec1, v52
	s_waitcnt lgkmcnt(6)
	v_add_f32_e32 v59, v43, v59
	v_cndmask_b32_e32 v59, v240, v59, vcc
	v_cmp_gt_u32_e32 vcc, 2.0, v238
	v_add_u32_e32 v239, 0xfffffeb1, v52
	s_waitcnt lgkmcnt(5)
	v_add_f32_e32 v62, v44, v62
	v_cndmask_b32_e32 v62, v240, v62, vcc
	v_cmp_gt_u32_e32 vcc, 2.0, v239
	v_add_u32_e32 v238, 0xfffffe61, v52
	s_waitcnt lgkmcnt(4)
	v_add_f32_e32 v61, v45, v61
	v_cndmask_b32_e32 v61, v240, v61, vcc
	v_cmp_gt_u32_e32 vcc, 2.0, v238
	v_add_u32_e32 v239, 0xfffffe51, v52
	s_waitcnt lgkmcnt(3)
	v_add_f32_e32 v64, v46, v64
	v_cndmask_b32_e32 v64, v240, v64, vcc
	v_cmp_gt_u32_e32 vcc, 2.0, v239
	v_add_u32_e32 v238, 0xfffffe41, v52
	s_waitcnt lgkmcnt(2)
	v_add_f32_e32 v63, v47, v63
	v_cndmask_b32_e32 v63, v240, v63, vcc
	v_cmp_gt_u32_e32 vcc, 2.0, v238
	v_add_u32_e32 v239, 0xfffffe31, v52
	s_waitcnt lgkmcnt(1)
	v_add_f32_e32 v124, v48, v124
	v_cndmask_b32_e32 v124, v240, v124, vcc
	v_cmp_gt_u32_e32 vcc, 2.0, v239
	s_nop 0
	s_waitcnt lgkmcnt(0)
	v_add_f32_e32 v65, v49, v65
	v_cndmask_b32_e32 v65, v240, v65, vcc
	v_sub_f32_e32 v50, v50, v119
	v_sub_f32_e32 v51, v51, v119
	v_sub_f32_e32 v52, v54, v119
	v_sub_f32_e32 v53, v53, v119
	v_sub_f32_e32 v54, v56, v119
	v_sub_f32_e32 v55, v55, v119
	v_sub_f32_e32 v56, v58, v119
	v_sub_f32_e32 v57, v57, v119
	v_sub_f32_e32 v58, v60, v119
	v_sub_f32_e32 v59, v59, v119
	v_sub_f32_e32 v60, v62, v119
	v_sub_f32_e32 v61, v61, v119
	v_sub_f32_e32 v62, v64, v119
	v_sub_f32_e32 v63, v63, v119
	v_sub_f32_e32 v64, v124, v119
	v_exp_f32_e32 v50, v50
	v_exp_f32_e32 v51, v51
	v_exp_f32_e32 v52, v52
	v_exp_f32_e32 v53, v53
	v_exp_f32_e32 v54, v54
	v_exp_f32_e32 v55, v55
	v_exp_f32_e32 v56, v56
	v_exp_f32_e32 v57, v57
	v_exp_f32_e32 v58, v58
	v_exp_f32_e32 v59, v59
	v_exp_f32_e32 v60, v60
	v_exp_f32_e32 v61, v61
	v_exp_f32_e32 v62, v62
	v_exp_f32_e32 v63, v63
	v_exp_f32_e32 v64, v64
	v_sub_f32_e32 v65, v65, v119
	s_mov_b64 s[18:19], 0

; __device__ __forceinline__ unsigned cvt_pk_bf16(float lo, float hi) { unsigned r; asm volatile("v_cvt_pk_bf16_f32 %0, %1, %2" : "=v"(r) : "v"(lo), "v"(hi)); return r; }
; #define MFMA32(a, b, c) __builtin_amdgcn_mfma_f32_32x32x16_bf16((a), (b), (c), 0, 0, 0)
; __device__ __forceinline__ void pv_tile(f32x16& o0, f32x16& o1, const f32x16& pr, const bf16x8 (&vf)[2][2]) {
; #pragma unroll
;     for (int s = 0; s < 2; ++s) {
;         u32x4 pk; pk.x = cvt_pk_bf16(pr[8 * s], pr[8 * s + 1]); pk.y = cvt_pk_bf16(pr[8 * s + 2], pr[8 * s + 3]); pk.z = cvt_pk_bf16(pr[8 * s + 4], pr[8 * s + 5]); pk.w = cvt_pk_bf16(pr[8 * s + 6], pr[8 * s + 7]);
;         const bf16x8 pb = __builtin_bit_cast(bf16x8, pk);
;         o0 = MFMA32(vf[0][s], pb, o0);
;         o1 = MFMA32(vf[1][s], pb, o1);
;     }
; }
; __device__ __forceinline__ void nsa_unit(const Params& p, int bg, int jq, LAS unsigned char* lds, int wave, int lane, bool build_lut) {
;     ...
;         for (int T = 0; T < ntile; ++T) {
; #pragma unroll
;             for (int ks = 0; ks < 4; ++ks) kf[ks] = kn[ks];
;             load_v(vf, vcmpT + (size_t)T * 2048, lane);
;             if (T + 1 < ntile) load_k(kn, kcmp + (size_t)(T + 1) * 2048, lane);
.LBB0_1145:
	s_or_b64 exec, exec, s[18:19]
	v_cvt_pk_bf16_f32 v36, v50, v51
	v_cvt_pk_bf16_f32 v37, v52, v53
	v_cvt_pk_bf16_f32 v38, v54, v55
	v_cvt_pk_bf16_f32 v39, v56, v57
	s_add_i32 s24, s24, 1
	s_waitcnt vmcnt(3)
	v_mfma_f32_32x32x16_bf16 v[18:33], v[106:109], v[36:39], v[18:33]
	s_addk_i32 s23, 0xfe00
	v_add_u32_e32 v123, 8, v123
	v_add_u32_e32 v121, 32, v121
	v_add_u32_e32 v122, 0xfffffe00, v122
	v_lshl_add_u64 v[116:117], v[116:117], 0, s[84:85]
	s_cmp_eq_u32 s22, s24
	s_waitcnt vmcnt(1)
	v_mfma_f32_32x32x16_bf16 v[2:17], v[110:113], v[36:39], v[2:17]
	v_cvt_pk_bf16_f32 v36, v58, v59
	v_cvt_pk_bf16_f32 v37, v60, v61
	v_cvt_pk_bf16_f32 v38, v62, v63
	v_cvt_pk_bf16_f32 v39, v64, v34
	s_nop 0
	v_mfma_f32_32x32x16_bf16 v[18:33], v[102:105], v[36:39], v[18:33]
	s_waitcnt vmcnt(0)
	v_mfma_f32_32x32x16_bf16 v[2:17], v[98:101], v[36:39], v[2:17]
	s_cbranch_scc1 .LBB0_1147
	s_branch .LBB0_1095
